# DA: all 16 P conversions stay in the softmax block, MFMA block carries no VALU (only MFMA + LDS reads + 4 row-sum MFMAs); on top of MLA/GEMM saddr
# speedup vs baseline: 1.0239x; 1.0024x over previous
.LBB0_599:
	s_barrier
	s_setprio 3
	ds_read_b64_tr_b16 v[194:195], v238 offset:0
	ds_read_b64_tr_b16 v[196:197], v238 offset:0x800
	ds_read_b64_tr_b16 v[198:199], v238 offset:0x200
	ds_read_b64_tr_b16 v[200:201], v238 offset:0xa00
	ds_read_b64_tr_b16 v[202:203], v238 offset:0x400
	ds_read_b64_tr_b16 v[204:205], v238 offset:0xc00
	ds_read_b64_tr_b16 v[206:207], v238 offset:0x600
	ds_read_b64_tr_b16 v[208:209], v238 offset:0xe00
	ds_read_b128 v[226:229], v188 offset:45056
	ds_read_b128 v[230:233], v189 offset:40960
	ds_read_b128 v[234:237], v189 offset:45056
	s_waitcnt lgkmcnt(9)
	v_mfma_f32_32x32x16_bf16 v[50:65], v[142:145], v[194:197], v[50:65]
	ds_read_b64_tr_b16 v[210:211], v238 offset:0x1000
	ds_read_b64_tr_b16 v[212:213], v238 offset:0x1800
	s_waitcnt lgkmcnt(9)
	v_mfma_f32_32x32x16_bf16 v[34:49], v[142:145], v[198:201], v[34:49]
	ds_read_b64_tr_b16 v[214:215], v238 offset:0x1200
	ds_read_b64_tr_b16 v[216:217], v238 offset:0x1a00
	s_waitcnt lgkmcnt(9)
	v_mfma_f32_32x32x16_bf16 v[18:33], v[142:145], v[202:205], v[18:33]
	ds_read_b64_tr_b16 v[218:219], v238 offset:0x1400
	ds_read_b64_tr_b16 v[220:221], v238 offset:0x1c00
	s_waitcnt lgkmcnt(9)
	v_mfma_f32_32x32x16_bf16 v[2:17], v[142:145], v[206:209], v[2:17]
	ds_read_b64_tr_b16 v[222:223], v238 offset:0x1600
	ds_read_b64_tr_b16 v[224:225], v238 offset:0x1e00
	v_mfma_f32_16x16x32_bf16 v[244:247], v[142:145], v[248:251], v[244:247]
	s_waitcnt lgkmcnt(6)
	v_mfma_f32_32x32x16_bf16 v[50:65], v[138:141], v[210:213], v[50:65]
	ds_read_b64_tr_b16 v[194:195], v238 offset:0x2000
	ds_read_b64_tr_b16 v[196:197], v238 offset:0x2800
	s_waitcnt lgkmcnt(6)
	v_mfma_f32_32x32x16_bf16 v[34:49], v[138:141], v[214:217], v[34:49]
	ds_read_b64_tr_b16 v[198:199], v238 offset:0x2200
	ds_read_b64_tr_b16 v[200:201], v238 offset:0x2a00
	s_waitcnt lgkmcnt(6)
	v_mfma_f32_32x32x16_bf16 v[18:33], v[138:141], v[218:221], v[18:33]
	ds_read_b64_tr_b16 v[202:203], v238 offset:0x2400
	ds_read_b64_tr_b16 v[204:205], v238 offset:0x2c00
	s_waitcnt lgkmcnt(6)
	v_mfma_f32_32x32x16_bf16 v[2:17], v[138:141], v[222:225], v[2:17]
	ds_read_b64_tr_b16 v[206:207], v238 offset:0x2600
	ds_read_b64_tr_b16 v[208:209], v238 offset:0x2e00
	v_mfma_f32_16x16x32_bf16 v[244:247], v[138:141], v[248:251], v[244:247]
	s_waitcnt lgkmcnt(6)
	v_mfma_f32_32x32x16_bf16 v[50:65], v[134:137], v[194:197], v[50:65]
	ds_read_b64_tr_b16 v[210:211], v238 offset:0x3000
	ds_read_b64_tr_b16 v[212:213], v238 offset:0x3800
	s_waitcnt lgkmcnt(6)
	v_mfma_f32_32x32x16_bf16 v[34:49], v[134:137], v[198:201], v[34:49]
	ds_read_b64_tr_b16 v[214:215], v238 offset:0x3200
	ds_read_b64_tr_b16 v[216:217], v238 offset:0x3a00
	s_waitcnt lgkmcnt(6)
	v_mfma_f32_32x32x16_bf16 v[18:33], v[134:137], v[202:205], v[18:33]
	ds_read_b64_tr_b16 v[218:219], v238 offset:0x3400
	ds_read_b64_tr_b16 v[220:221], v238 offset:0x3c00
	s_waitcnt lgkmcnt(6)
	v_mfma_f32_32x32x16_bf16 v[2:17], v[134:137], v[206:209], v[2:17]
	ds_read_b64_tr_b16 v[222:223], v238 offset:0x3600
	ds_read_b64_tr_b16 v[224:225], v238 offset:0x3e00
	v_mfma_f32_16x16x32_bf16 v[244:247], v[134:137], v[248:251], v[244:247]
	s_waitcnt lgkmcnt(6)
	v_mfma_f32_32x32x16_bf16 v[50:65], v[130:133], v[210:213], v[50:65]
	ds_read_b128 v[82:85], v188 offset:40960
	ds_read_b128 v[194:197], v190 offset:40960
	s_waitcnt lgkmcnt(6)
	v_mfma_f32_32x32x16_bf16 v[34:49], v[130:133], v[214:217], v[34:49]
	ds_read_b128 v[198:201], v190 offset:45056
	s_waitcnt lgkmcnt(5)
	v_mfma_f32_32x32x16_bf16 v[18:33], v[130:133], v[218:221], v[18:33]
	ds_read_b128 v[202:205], v191 offset:40960
	s_waitcnt lgkmcnt(4)
	v_mfma_f32_32x32x16_bf16 v[2:17], v[130:133], v[222:225], v[2:17]
	ds_read_b128 v[206:209], v191 offset:45056
	v_mfma_f32_16x16x32_bf16 v[244:247], v[130:133], v[248:251], v[244:247]
	s_waitcnt lgkmcnt(4)
	v_mfma_f32_32x32x16_bf16 v[98:113], v[82:85], v[126:129], v[66:81]
	v_mfma_f32_32x32x16_bf16 v[82:97], v[226:229], v[126:129], v[66:81]
	v_mfma_f32_32x32x16_bf16 v[98:113], v[230:233], v[122:125], v[98:113]
	v_mfma_f32_32x32x16_bf16 v[82:97], v[234:237], v[122:125], v[82:97]
	s_waitcnt lgkmcnt(3)
	v_mfma_f32_32x32x16_bf16 v[98:113], v[194:197], v[118:121], v[98:113]
	s_waitcnt lgkmcnt(2)
	v_mfma_f32_32x32x16_bf16 v[82:97], v[198:201], v[118:121], v[82:97]
	s_waitcnt lgkmcnt(1)
	v_mfma_f32_32x32x16_bf16 v[98:113], v[202:205], v[114:117], v[98:113]
	s_waitcnt lgkmcnt(0)
	v_mfma_f32_32x32x16_bf16 v[82:97], v[206:209], v[114:117], v[82:97]

.LBB0_612:
	s_barrier
	s_setprio 3
	v_add_u32_e32 v197, s75, v193
	ds_read_b64_tr_b16 v[198:199], v197 offset:0
	ds_read_b64_tr_b16 v[200:201], v197 offset:0x800
	ds_read_b64_tr_b16 v[202:203], v197 offset:0x200
	ds_read_b64_tr_b16 v[204:205], v197 offset:0xa00
	ds_read_b64_tr_b16 v[206:207], v197 offset:0x400
	ds_read_b64_tr_b16 v[208:209], v197 offset:0xc00
	ds_read_b64_tr_b16 v[210:211], v197 offset:0x600
	ds_read_b64_tr_b16 v[212:213], v197 offset:0xe00
	ds_read_b128 v[230:233], v188 offset:36864
	ds_read_b128 v[234:237], v189 offset:32768
	ds_read_b128 v[238:241], v189 offset:36864
	s_waitcnt lgkmcnt(9)
	v_mfma_f32_32x32x16_bf16 v[50:65], v[142:145], v[198:201], v[50:65]
	ds_read_b64_tr_b16 v[214:215], v197 offset:0x1000
	ds_read_b64_tr_b16 v[216:217], v197 offset:0x1800
	s_waitcnt lgkmcnt(9)
	v_mfma_f32_32x32x16_bf16 v[34:49], v[142:145], v[202:205], v[34:49]
	ds_read_b64_tr_b16 v[218:219], v197 offset:0x1200
	ds_read_b64_tr_b16 v[220:221], v197 offset:0x1a00
	s_waitcnt lgkmcnt(9)
	v_mfma_f32_32x32x16_bf16 v[18:33], v[142:145], v[206:209], v[18:33]
	ds_read_b64_tr_b16 v[222:223], v197 offset:0x1400
	ds_read_b64_tr_b16 v[224:225], v197 offset:0x1c00
	s_waitcnt lgkmcnt(9)
	v_mfma_f32_32x32x16_bf16 v[2:17], v[142:145], v[210:213], v[2:17]
	ds_read_b64_tr_b16 v[226:227], v197 offset:0x1600
	ds_read_b64_tr_b16 v[228:229], v197 offset:0x1e00
	v_mfma_f32_16x16x32_bf16 v[244:247], v[142:145], v[248:251], v[244:247]
	s_waitcnt lgkmcnt(6)
	v_mfma_f32_32x32x16_bf16 v[50:65], v[138:141], v[214:217], v[50:65]
	ds_read_b64_tr_b16 v[198:199], v197 offset:0x2000
	ds_read_b64_tr_b16 v[200:201], v197 offset:0x2800
	s_waitcnt lgkmcnt(6)
	v_mfma_f32_32x32x16_bf16 v[34:49], v[138:141], v[218:221], v[34:49]
	ds_read_b64_tr_b16 v[202:203], v197 offset:0x2200
	ds_read_b64_tr_b16 v[204:205], v197 offset:0x2a00
	s_waitcnt lgkmcnt(6)
	v_mfma_f32_32x32x16_bf16 v[18:33], v[138:141], v[222:225], v[18:33]
	ds_read_b64_tr_b16 v[206:207], v197 offset:0x2400
	ds_read_b64_tr_b16 v[208:209], v197 offset:0x2c00
	s_waitcnt lgkmcnt(6)
	v_mfma_f32_32x32x16_bf16 v[2:17], v[138:141], v[226:229], v[2:17]
	ds_read_b64_tr_b16 v[210:211], v197 offset:0x2600
	ds_read_b64_tr_b16 v[212:213], v197 offset:0x2e00
	v_mfma_f32_16x16x32_bf16 v[244:247], v[138:141], v[248:251], v[244:247]
	s_waitcnt lgkmcnt(6)
	v_mfma_f32_32x32x16_bf16 v[50:65], v[134:137], v[198:201], v[50:65]
	ds_read_b64_tr_b16 v[214:215], v197 offset:0x3000
	ds_read_b64_tr_b16 v[216:217], v197 offset:0x3800
	s_waitcnt lgkmcnt(6)
	v_mfma_f32_32x32x16_bf16 v[34:49], v[134:137], v[202:205], v[34:49]
	ds_read_b64_tr_b16 v[218:219], v197 offset:0x3200
	ds_read_b64_tr_b16 v[220:221], v197 offset:0x3a00
	s_waitcnt lgkmcnt(6)
	v_mfma_f32_32x32x16_bf16 v[18:33], v[134:137], v[206:209], v[18:33]
	ds_read_b64_tr_b16 v[222:223], v197 offset:0x3400
	ds_read_b64_tr_b16 v[224:225], v197 offset:0x3c00
	s_waitcnt lgkmcnt(6)
	v_mfma_f32_32x32x16_bf16 v[2:17], v[134:137], v[210:213], v[2:17]
	ds_read_b64_tr_b16 v[226:227], v197 offset:0x3600
	ds_read_b64_tr_b16 v[228:229], v197 offset:0x3e00
	v_mfma_f32_16x16x32_bf16 v[244:247], v[134:137], v[248:251], v[244:247]
	s_waitcnt lgkmcnt(6)
	v_mfma_f32_32x32x16_bf16 v[50:65], v[130:133], v[214:217], v[50:65]
	ds_read_b128 v[82:85], v188 offset:32768
	ds_read_b128 v[198:201], v190 offset:32768
	s_waitcnt lgkmcnt(6)
	v_mfma_f32_32x32x16_bf16 v[34:49], v[130:133], v[218:221], v[34:49]
	ds_read_b128 v[202:205], v190 offset:36864
	s_waitcnt lgkmcnt(5)
	v_mfma_f32_32x32x16_bf16 v[18:33], v[130:133], v[222:225], v[18:33]
	ds_read_b128 v[206:209], v191 offset:32768
	s_waitcnt lgkmcnt(4)
	v_mfma_f32_32x32x16_bf16 v[2:17], v[130:133], v[226:229], v[2:17]
	ds_read_b128 v[210:213], v191 offset:36864
	v_mfma_f32_16x16x32_bf16 v[244:247], v[130:133], v[248:251], v[244:247]
	s_waitcnt lgkmcnt(4)
	v_mfma_f32_32x32x16_bf16 v[98:113], v[82:85], v[126:129], v[66:81]
	v_mfma_f32_32x32x16_bf16 v[82:97], v[230:233], v[126:129], v[66:81]
	v_mfma_f32_32x32x16_bf16 v[98:113], v[234:237], v[122:125], v[98:113]
	v_mfma_f32_32x32x16_bf16 v[82:97], v[238:241], v[122:125], v[82:97]
	s_waitcnt lgkmcnt(3)
	v_mfma_f32_32x32x16_bf16 v[98:113], v[198:201], v[118:121], v[98:113]
	s_waitcnt lgkmcnt(2)
	v_mfma_f32_32x32x16_bf16 v[82:97], v[202:205], v[118:121], v[82:97]
	s_waitcnt lgkmcnt(1)
	v_mfma_f32_32x32x16_bf16 v[98:113], v[206:209], v[114:117], v[98:113]
	s_waitcnt lgkmcnt(0)
	v_mfma_f32_32x32x16_bf16 v[82:97], v[210:213], v[114:117], v[82:97]
	s_and_b64 vcc, exec, s[6:7]
	s_cbranch_vccnz .LBB0_614
	s_waitcnt vmcnt(1)

.Lrot_da_exit:
	s_barrier
	s_nop 1
	v_mfma_f32_16x16x32_bf16 v[244:247], v[142:145], v[248:251], v[244:247]
	v_mfma_f32_16x16x32_bf16 v[244:247], v[138:141], v[248:251], v[244:247]
	v_mfma_f32_16x16x32_bf16 v[244:247], v[134:137], v[248:251], v[244:247]
	v_mfma_f32_16x16x32_bf16 v[244:247], v[130:133], v[248:251], v[244:247]
	s_branch .LBB0_629
